# GEMM K-loops: the clamped re-read loads past the last K-tile (never stored to LDS, kept only for uniform vmcnt counting) are issued with a single active lane
# speedup vs baseline: 1.0035x; 1.0035x over previous
; #define LOADS(S, k0) { LD1(S, 0, k0) LD1(S, 1, k0) LD1(S, 2, k0) LD1(S, 3, k0) }
; #define STORES(S, buf) { ST1(S, 0, buf) ST1(S, 1, buf) ST1(S, 2, buf) ST1(S, 3, buf) }
; template <int AMODE, bool F16 = false, bool MASK = false>
; DI void gemm_tile(const bf16_t* __restrict__ Ab, int lda, int row0, int rlo, int rhi,
;                   const bf16_t* __restrict__ Bt, int ldb, int K, char* smem, f32x16 (&acc)[2][2]) {
;     ...
;     for (int kt = 0; kt < nk; kt += 2) {
;         COMPUTE(0);
;         STORES(p1, 1);
;         LOADS(p1, min((kt + 3) * 64, klast));
;         __syncthreads();
;         COMPUTE(1);
;         if (kt + 2 < nk) STORES(p0, 0);
;         LOADS(p0, min((kt + 4) * 64, klast));
;         __syncthreads();
.LBB0_34:
	s_min_u32 s35, s13, 0x9c0
	s_lshl_b32 s44, s35, 1
	s_add_i32 s56, s44, 0x200
	s_mov_b32 s45, s57
	s_mov_b64 s[100:101], exec
	s_cmp_gt_u32 s13, 0x9c0
	s_cselect_b64 exec, 1, s[100:101]
	v_lshl_add_u64 v[76:77], v[32:33], 0, s[56:57]
	v_lshl_add_u64 v[88:89], v[132:133], 0, s[44:45]
	global_load_dwordx4 v[76:79], v[76:77], off
	s_nop 0
	global_load_dwordx4 v[92:95], v[88:89], off offset:512
	v_lshl_add_u64 v[88:89], v[140:141], 0, s[56:57]
	v_lshl_add_u64 v[90:91], v[134:135], 0, s[44:45]
	v_lshl_add_u64 v[96:97], v[142:143], 0, s[56:57]
	global_load_dwordx4 v[104:107], v[88:89], off
	s_nop 0
	global_load_dwordx4 v[88:91], v[90:91], off offset:512
	v_lshl_add_u64 v[98:99], v[136:137], 0, s[44:45]
	global_load_dwordx4 v[120:123], v[96:97], off
	global_load_dwordx4 v[124:127], v[98:99], off offset:512
	v_lshl_add_u64 v[96:97], v[144:145], 0, s[56:57]
	s_waitcnt vmcnt(14)
	v_lshl_add_u64 v[128:129], v[138:139], 0, s[44:45]
	global_load_dwordx4 v[96:99], v[96:97], off
	s_nop 0
	global_load_dwordx4 v[128:131], v[128:129], off offset:512
	s_mov_b64 exec, s[100:101]
	s_add_i32 s34, s34, 2
	s_andn2_b64 vcc, exec, s[42:43]
	s_addk_i32 s13, 0x80
	s_waitcnt lgkmcnt(0)
	s_barrier
	s_cbranch_vccz .LBB0_37
; #define LOADS(S, k0) { LD1(S, 0, k0) LD1(S, 1, k0) LD1(S, 2, k0) LD1(S, 3, k0) }
; #define STORES(S, buf) { ST1(S, 0, buf) ST1(S, 1, buf) ST1(S, 2, buf) ST1(S, 3, buf) }
; template <int AMODE, bool F16 = false, bool MASK = false>
; DI void gemm_tile(const bf16_t* __restrict__ Ab, int lda, int row0, int rlo, int rhi,
;                   const bf16_t* __restrict__ Bt, int ldb, int K, char* smem, f32x16 (&acc)[2][2]) {
;     ...
;     for (int kt = 0; kt < nk; kt += 2) {
;         COMPUTE(0);
;         STORES(p1, 1);
;         LOADS(p1, min((kt + 3) * 64, klast));
;         __syncthreads();
;         COMPUTE(1);
;         if (kt + 2 < nk) STORES(p0, 0);
;         LOADS(p0, min((kt + 4) * 64, klast));
;         __syncthreads();
.LBB0_35:
	ds_read_b128 v[150:153], v34
	ds_read_b128 v[154:157], v34 offset:32
	ds_read_b128 v[158:161], v34 offset:4608
	ds_read_b128 v[162:165], v34 offset:4640
	ds_read_b128 v[166:169], v147 offset:36864
	ds_read_b128 v[170:173], v147 offset:36896
	ds_read_b128 v[174:177], v147 offset:41472
	ds_read_b128 v[178:181], v147 offset:41504
	s_setprio 1
	s_waitcnt lgkmcnt(3)
	v_mfma_f32_32x32x16_bf16 v[52:67], v[150:153], v[166:169], v[52:67]
	s_waitcnt lgkmcnt(1)
	v_mfma_f32_32x32x16_bf16 v[36:51], v[150:153], v[174:177], v[36:51]
	v_mfma_f32_32x32x16_bf16 v[16:31], v[158:161], v[166:169], v[16:31]
	v_mfma_f32_32x32x16_bf16 v[0:15], v[158:161], v[174:177], v[0:15]
	s_setprio 0
	ds_read_b128 v[150:153], v34 offset:64
	ds_read_b128 v[158:161], v34 offset:4672
	ds_read_b128 v[166:169], v147 offset:36928
	ds_read_b128 v[174:177], v147 offset:41536
	s_setprio 1
	v_mfma_f32_32x32x16_bf16 v[52:67], v[154:157], v[170:173], v[52:67]
	s_waitcnt lgkmcnt(4)
	v_mfma_f32_32x32x16_bf16 v[36:51], v[154:157], v[178:181], v[36:51]
	v_mfma_f32_32x32x16_bf16 v[16:31], v[162:165], v[170:173], v[16:31]
	v_mfma_f32_32x32x16_bf16 v[0:15], v[162:165], v[178:181], v[0:15]
	s_setprio 0
	ds_read_b128 v[154:157], v34 offset:96
	ds_read_b128 v[162:165], v34 offset:4704
	ds_read_b128 v[170:173], v147 offset:36960
	ds_read_b128 v[178:181], v147 offset:41568
	s_setprio 1
	s_waitcnt lgkmcnt(5)
	v_mfma_f32_32x32x16_bf16 v[52:67], v[150:153], v[166:169], v[52:67]
	s_waitcnt lgkmcnt(4)
	v_mfma_f32_32x32x16_bf16 v[36:51], v[150:153], v[174:177], v[36:51]
	v_mfma_f32_32x32x16_bf16 v[16:31], v[158:161], v[166:169], v[16:31]
	v_mfma_f32_32x32x16_bf16 v[0:15], v[158:161], v[174:177], v[0:15]
	s_setprio 0
	s_setprio 1
	s_waitcnt lgkmcnt(1)
	v_mfma_f32_32x32x16_bf16 v[52:67], v[154:157], v[170:173], v[52:67]
	s_waitcnt lgkmcnt(0)
	v_mfma_f32_32x32x16_bf16 v[36:51], v[154:157], v[178:181], v[36:51]
	v_mfma_f32_32x32x16_bf16 v[16:31], v[162:165], v[170:173], v[16:31]
	v_mfma_f32_32x32x16_bf16 v[0:15], v[162:165], v[178:181], v[0:15]
	s_setprio 0
	s_min_u32 s35, s13, 0xa00
	s_lshl_b32 s42, s35, 1
	s_add_i32 s56, s42, 0x180
	s_mov_b32 s43, s57
	s_waitcnt vmcnt(1)
	ds_write_b128 v146, v[108:111] offset:18432
	ds_write_b128 v146, v[84:87] offset:55296
	ds_write_b128 v146, v[100:103] offset:23040
	ds_write_b128 v146, v[68:71] offset:59904
	ds_write_b128 v146, v[112:115] offset:27648
	ds_write_b128 v146, v[116:119] offset:64512
	ds_write_b128 v146, v[80:83] offset:32256
	ds_write_b128 v148, v[72:75] offset:13824
	s_mov_b64 s[100:101], exec
	s_cmp_gt_u32 s13, 0xa00
	s_cselect_b64 exec, 1, s[100:101]
	v_lshl_add_u64 v[68:69], v[32:33], 0, s[56:57]
	v_lshl_add_u64 v[70:71], v[132:133], 0, s[42:43]
	global_load_dwordx4 v[108:111], v[68:69], off
	global_load_dwordx4 v[84:87], v[70:71], off offset:384
	v_lshl_add_u64 v[68:69], v[140:141], 0, s[56:57]
	v_lshl_add_u64 v[70:71], v[134:135], 0, s[42:43]
	v_lshl_add_u64 v[72:73], v[142:143], 0, s[56:57]
	v_lshl_add_u64 v[74:75], v[136:137], 0, s[42:43]
	global_load_dwordx4 v[100:103], v[68:69], off
	s_nop 0
	global_load_dwordx4 v[68:71], v[70:71], off offset:384
	s_nop 0
	global_load_dwordx4 v[112:115], v[72:73], off
	global_load_dwordx4 v[116:119], v[74:75], off offset:384
	v_lshl_add_u64 v[72:73], v[144:145], 0, s[56:57]
	v_lshl_add_u64 v[74:75], v[138:139], 0, s[42:43]
	global_load_dwordx4 v[80:83], v[72:73], off
	s_nop 0
	global_load_dwordx4 v[72:75], v[74:75], off offset:384
	s_mov_b64 exec, s[100:101]
	s_waitcnt lgkmcnt(0)
	s_barrier
	ds_read_b128 v[150:153], v34 offset:18432
	ds_read_b128 v[154:157], v34 offset:18464
	ds_read_b128 v[158:161], v34 offset:23040
	ds_read_b128 v[162:165], v34 offset:23072
	ds_read_b128 v[166:169], v147 offset:55296
	ds_read_b128 v[170:173], v147 offset:55328
	ds_read_b128 v[174:177], v147 offset:59904
	ds_read_b128 v[178:181], v147 offset:59936
	s_setprio 1
	s_waitcnt lgkmcnt(3)
	v_mfma_f32_32x32x16_bf16 v[52:67], v[150:153], v[166:169], v[52:67]
	s_waitcnt lgkmcnt(1)
	v_mfma_f32_32x32x16_bf16 v[36:51], v[150:153], v[174:177], v[36:51]
	v_mfma_f32_32x32x16_bf16 v[16:31], v[158:161], v[166:169], v[16:31]
	v_mfma_f32_32x32x16_bf16 v[0:15], v[158:161], v[174:177], v[0:15]
	s_setprio 0
	ds_read_b128 v[150:153], v34 offset:18496
	ds_read_b128 v[158:161], v34 offset:23104
	ds_read_b128 v[166:169], v147 offset:55360
	ds_read_b128 v[174:177], v147 offset:59968
	s_setprio 1
	v_mfma_f32_32x32x16_bf16 v[52:67], v[154:157], v[170:173], v[52:67]
	s_waitcnt lgkmcnt(4)
	v_mfma_f32_32x32x16_bf16 v[36:51], v[154:157], v[178:181], v[36:51]
	v_mfma_f32_32x32x16_bf16 v[16:31], v[162:165], v[170:173], v[16:31]
	v_mfma_f32_32x32x16_bf16 v[0:15], v[162:165], v[178:181], v[0:15]
	s_setprio 0
	ds_read_b128 v[154:157], v34 offset:18528
	ds_read_b128 v[162:165], v34 offset:23136
	ds_read_b128 v[170:173], v147 offset:55392
	ds_read_b128 v[178:181], v147 offset:60000
	s_setprio 1
	s_waitcnt lgkmcnt(5)
	v_mfma_f32_32x32x16_bf16 v[52:67], v[150:153], v[166:169], v[52:67]
	s_waitcnt lgkmcnt(4)
	v_mfma_f32_32x32x16_bf16 v[36:51], v[150:153], v[174:177], v[36:51]
	v_mfma_f32_32x32x16_bf16 v[16:31], v[158:161], v[166:169], v[16:31]
	v_mfma_f32_32x32x16_bf16 v[0:15], v[158:161], v[174:177], v[0:15]
	s_setprio 0
	s_setprio 1
	s_waitcnt lgkmcnt(1)
	v_mfma_f32_32x32x16_bf16 v[52:67], v[154:157], v[170:173], v[52:67]
	s_waitcnt lgkmcnt(0)
	v_mfma_f32_32x32x16_bf16 v[36:51], v[154:157], v[178:181], v[36:51]
	v_mfma_f32_32x32x16_bf16 v[16:31], v[162:165], v[170:173], v[16:31]
	v_mfma_f32_32x32x16_bf16 v[0:15], v[162:165], v[178:181], v[0:15]
	s_setprio 0
	s_cmp_gt_u32 s34, 41
	s_cselect_b64 s[42:43], -1, 0
	s_and_b64 vcc, exec, s[42:43]
	s_cbranch_vccnz .LBB0_34
	ds_write_b128 v146, v[76:79]
	ds_write_b128 v146, v[92:95] offset:36864
	ds_write_b128 v146, v[104:107] offset:4608
	ds_write_b128 v146, v[88:91] offset:41472
	ds_write_b128 v146, v[120:123] offset:9216
	ds_write_b128 v146, v[124:127] offset:46080
	ds_write_b128 v146, v[96:99] offset:13824
	s_waitcnt vmcnt(8)
	ds_write_b128 v146, v[128:131] offset:50688
	s_branch .LBB0_34

; #define LOADS(S, k0) { LD1(S, 0, k0) LD1(S, 1, k0) LD1(S, 2, k0) LD1(S, 3, k0) }
; #define STORES(S, buf) { ST1(S, 0, buf) ST1(S, 1, buf) ST1(S, 2, buf) ST1(S, 3, buf) }
; template <int AMODE, bool F16 = false, bool MASK = false>
; DI void gemm_tile(const bf16_t* __restrict__ Ab, int lda, int row0, int rlo, int rhi,
;                   const bf16_t* __restrict__ Bt, int ldb, int K, char* smem, f32x16 (&acc)[2][2]) {
;     ...
;     for (int kt = 0; kt < nk; kt += 2) {
;         COMPUTE(0);
;         STORES(p1, 1);
;         LOADS(p1, min((kt + 3) * 64, klast));
;         __syncthreads();
;         COMPUTE(1);
;         if (kt + 2 < nk) STORES(p0, 0);
;         LOADS(p0, min((kt + 4) * 64, klast));
;         __syncthreads();
.LBB0_68:
	s_min_u32 s19, s15, 0x2c0
	s_lshl_b32 s34, s19, 1
	s_add_i32 s56, s34, 0x200
	s_mov_b32 s35, s57
	s_mov_b64 s[100:101], exec
	s_cmp_gt_u32 s15, 0x2c0
	s_cselect_b64 exec, 1, s[100:101]
	v_lshl_add_u64 v[92:93], v[148:149], 0, s[56:57]
	v_lshl_add_u64 v[94:95], v[156:157], 0, s[34:35]
	v_lshl_add_u64 v[100:101], v[150:151], 0, s[56:57]
	v_lshl_add_u64 v[102:103], v[158:159], 0, s[34:35]
	global_load_dwordx4 v[96:99], v[92:93], off
	s_nop 0
	global_load_dwordx4 v[92:95], v[94:95], off offset:512
	s_nop 0
	global_load_dwordx4 v[108:111], v[100:101], off
	global_load_dwordx4 v[112:115], v[102:103], off offset:512
	v_lshl_add_u64 v[100:101], v[152:153], 0, s[56:57]
	v_lshl_add_u64 v[102:103], v[160:161], 0, s[34:35]
	v_lshl_add_u64 v[124:125], v[154:155], 0, s[56:57]
	s_waitcnt vmcnt(12)
	v_lshl_add_u64 v[128:129], v[162:163], 0, s[34:35]
	global_load_dwordx4 v[116:119], v[100:101], off
	s_nop 0
	global_load_dwordx4 v[100:103], v[102:103], off offset:512
	s_nop 0
	global_load_dwordx4 v[124:127], v[124:125], off
	s_nop 0
	global_load_dwordx4 v[128:131], v[128:129], off offset:512
	s_mov_b64 exec, s[100:101]
	s_add_i32 s18, s18, 2
	s_andn2_b64 vcc, exec, s[16:17]
	s_addk_i32 s15, 0x80
	s_waitcnt lgkmcnt(0)
	s_barrier
	s_cbranch_vccz .LBB0_72
; #define LOADS(S, k0) { LD1(S, 0, k0) LD1(S, 1, k0) LD1(S, 2, k0) LD1(S, 3, k0) }
; #define STORES(S, buf) { ST1(S, 0, buf) ST1(S, 1, buf) ST1(S, 2, buf) ST1(S, 3, buf) }
; template <int AMODE, bool F16 = false, bool MASK = false>
; DI void gemm_tile(const bf16_t* __restrict__ Ab, int lda, int row0, int rlo, int rhi,
;                   const bf16_t* __restrict__ Bt, int ldb, int K, char* smem, f32x16 (&acc)[2][2]) {
;     ...
;     for (int kt = 0; kt < nk; kt += 2) {
;         COMPUTE(0);
;         STORES(p1, 1);
;         LOADS(p1, min((kt + 3) * 64, klast));
;         __syncthreads();
;         COMPUTE(1);
;         if (kt + 2 < nk) STORES(p0, 0);
;         LOADS(p0, min((kt + 4) * 64, klast));
;         __syncthreads();
.LBB0_69:
	ds_read_b128 v[170:173], v166
	ds_read_b128 v[174:177], v166 offset:32
	ds_read_b128 v[178:181], v166 offset:4608
	ds_read_b128 v[198:201], v166 offset:4640
	ds_read_b128 v[202:205], v167 offset:36864
	ds_read_b128 v[206:209], v167 offset:36896
	ds_read_b128 v[210:213], v167 offset:41472
	ds_read_b128 v[214:217], v167 offset:41504
	s_setprio 1
	s_waitcnt lgkmcnt(3)
	v_mfma_f32_32x32x16_f16 v[52:67], v[170:173], v[202:205], v[52:67]
	s_waitcnt lgkmcnt(1)
	v_mfma_f32_32x32x16_f16 v[36:51], v[170:173], v[210:213], v[36:51]
	v_mfma_f32_32x32x16_f16 v[16:31], v[178:181], v[202:205], v[16:31]
	v_mfma_f32_32x32x16_f16 v[0:15], v[178:181], v[210:213], v[0:15]
	s_setprio 0
	ds_read_b128 v[170:173], v166 offset:64
	ds_read_b128 v[178:181], v166 offset:4672
	ds_read_b128 v[202:205], v167 offset:36928
	ds_read_b128 v[210:213], v167 offset:41536
	s_setprio 1
	v_mfma_f32_32x32x16_f16 v[52:67], v[174:177], v[206:209], v[52:67]
	s_waitcnt lgkmcnt(4)
	v_mfma_f32_32x32x16_f16 v[36:51], v[174:177], v[214:217], v[36:51]
	v_mfma_f32_32x32x16_f16 v[16:31], v[198:201], v[206:209], v[16:31]
	v_mfma_f32_32x32x16_f16 v[0:15], v[198:201], v[214:217], v[0:15]
	s_setprio 0
	ds_read_b128 v[174:177], v166 offset:96
	ds_read_b128 v[198:201], v166 offset:4704
	ds_read_b128 v[206:209], v167 offset:36960
	ds_read_b128 v[214:217], v167 offset:41568
	s_setprio 1
	s_waitcnt lgkmcnt(5)
	v_mfma_f32_32x32x16_f16 v[52:67], v[170:173], v[202:205], v[52:67]
	s_waitcnt lgkmcnt(4)
	v_mfma_f32_32x32x16_f16 v[36:51], v[170:173], v[210:213], v[36:51]
	v_mfma_f32_32x32x16_f16 v[16:31], v[178:181], v[202:205], v[16:31]
	v_mfma_f32_32x32x16_f16 v[0:15], v[178:181], v[210:213], v[0:15]
	s_setprio 0
	s_setprio 1
	s_waitcnt lgkmcnt(1)
	v_mfma_f32_32x32x16_f16 v[52:67], v[174:177], v[206:209], v[52:67]
	s_waitcnt lgkmcnt(0)
	v_mfma_f32_32x32x16_f16 v[36:51], v[174:177], v[214:217], v[36:51]
	v_mfma_f32_32x32x16_f16 v[16:31], v[198:201], v[206:209], v[16:31]
	v_mfma_f32_32x32x16_f16 v[0:15], v[198:201], v[214:217], v[0:15]
	s_setprio 0
	s_min_u32 s16, s15, 0x300
	s_lshl_b32 s16, s16, 1
	s_add_i32 s56, s16, 0x180
	s_mov_b32 s17, s57
	s_waitcnt vmcnt(13)
	ds_write_b128 v34, v[76:79] offset:18432
	ds_write_b128 v34, v[72:75] offset:55296
	s_waitcnt vmcnt(12)
	ds_write_b128 v34, v[80:83] offset:23040
	s_waitcnt vmcnt(5)
	ds_write_b128 v34, v[104:107] offset:59904
	ds_write_b128 v34, v[84:87] offset:27648
	ds_write_b128 v34, v[68:71] offset:64512
	ds_write_b128 v34, v[88:91] offset:32256
	s_waitcnt vmcnt(1)
	ds_write_b128 v168, v[120:123] offset:13824
	s_mov_b64 s[100:101], exec
	s_cmp_gt_u32 s15, 0x300
	s_cselect_b64 exec, 1, s[100:101]
	v_lshl_add_u64 v[68:69], v[148:149], 0, s[56:57]
	v_lshl_add_u64 v[70:71], v[156:157], 0, s[16:17]
	global_load_dwordx4 v[76:79], v[68:69], off
	global_load_dwordx4 v[72:75], v[70:71], off offset:384
	v_lshl_add_u64 v[68:69], v[150:151], 0, s[56:57]
	v_lshl_add_u64 v[70:71], v[158:159], 0, s[16:17]
	global_load_dwordx4 v[80:83], v[68:69], off
	global_load_dwordx4 v[104:107], v[70:71], off offset:384
	v_lshl_add_u64 v[68:69], v[152:153], 0, s[56:57]
	v_lshl_add_u64 v[70:71], v[160:161], 0, s[16:17]
	v_lshl_add_u64 v[88:89], v[154:155], 0, s[56:57]
	v_lshl_add_u64 v[120:121], v[162:163], 0, s[16:17]
	global_load_dwordx4 v[84:87], v[68:69], off
	s_nop 0
	global_load_dwordx4 v[68:71], v[70:71], off offset:384
	s_nop 0
	global_load_dwordx4 v[88:91], v[88:89], off
	s_nop 0
	global_load_dwordx4 v[120:123], v[120:121], off offset:384
	s_mov_b64 exec, s[100:101]
	s_waitcnt lgkmcnt(0)
	s_barrier
	ds_read_b128 v[170:173], v166 offset:18432
	ds_read_b128 v[174:177], v166 offset:18464
	ds_read_b128 v[178:181], v166 offset:23040
	ds_read_b128 v[198:201], v166 offset:23072
	ds_read_b128 v[202:205], v167 offset:55296
	ds_read_b128 v[206:209], v167 offset:55328
	ds_read_b128 v[210:213], v167 offset:59904
	ds_read_b128 v[214:217], v167 offset:59936
	s_setprio 1
	s_waitcnt lgkmcnt(3)
	v_mfma_f32_32x32x16_f16 v[52:67], v[170:173], v[202:205], v[52:67]
	s_waitcnt lgkmcnt(1)
	v_mfma_f32_32x32x16_f16 v[36:51], v[170:173], v[210:213], v[36:51]
	v_mfma_f32_32x32x16_f16 v[16:31], v[178:181], v[202:205], v[16:31]
	v_mfma_f32_32x32x16_f16 v[0:15], v[178:181], v[210:213], v[0:15]
	s_setprio 0
	ds_read_b128 v[170:173], v166 offset:18496
	ds_read_b128 v[178:181], v166 offset:23104
	ds_read_b128 v[202:205], v167 offset:55360
	ds_read_b128 v[210:213], v167 offset:59968
	s_setprio 1
	v_mfma_f32_32x32x16_f16 v[52:67], v[174:177], v[206:209], v[52:67]
	s_waitcnt lgkmcnt(4)
	v_mfma_f32_32x32x16_f16 v[36:51], v[174:177], v[214:217], v[36:51]
	v_mfma_f32_32x32x16_f16 v[16:31], v[198:201], v[206:209], v[16:31]
	v_mfma_f32_32x32x16_f16 v[0:15], v[198:201], v[214:217], v[0:15]
	s_setprio 0
	ds_read_b128 v[174:177], v166 offset:18528
	ds_read_b128 v[198:201], v166 offset:23136
	ds_read_b128 v[206:209], v167 offset:55392
	ds_read_b128 v[214:217], v167 offset:60000
	s_setprio 1
	s_waitcnt lgkmcnt(5)
	v_mfma_f32_32x32x16_f16 v[52:67], v[170:173], v[202:205], v[52:67]
	s_waitcnt lgkmcnt(4)
	v_mfma_f32_32x32x16_f16 v[36:51], v[170:173], v[210:213], v[36:51]
	v_mfma_f32_32x32x16_f16 v[16:31], v[178:181], v[202:205], v[16:31]
	v_mfma_f32_32x32x16_f16 v[0:15], v[178:181], v[210:213], v[0:15]
	s_setprio 0
	s_setprio 1
	s_waitcnt lgkmcnt(1)
	v_mfma_f32_32x32x16_f16 v[52:67], v[174:177], v[206:209], v[52:67]
	s_waitcnt lgkmcnt(0)
	v_mfma_f32_32x32x16_f16 v[36:51], v[174:177], v[214:217], v[36:51]
	v_mfma_f32_32x32x16_f16 v[16:31], v[198:201], v[206:209], v[16:31]
	v_mfma_f32_32x32x16_f16 v[0:15], v[198:201], v[214:217], v[0:15]
	s_setprio 0
	s_cmp_gt_u32 s18, 13
	s_cselect_b64 s[16:17], -1, 0
	s_and_b64 vcc, exec, s[16:17]
	s_cbranch_vccnz .LBB0_68
	ds_write_b128 v34, v[96:99]
	ds_write_b128 v34, v[92:95] offset:36864
	ds_write_b128 v34, v[108:111] offset:4608
	ds_write_b128 v34, v[112:115] offset:41472
	ds_write_b128 v34, v[116:119] offset:9216
	ds_write_b128 v34, v[100:103] offset:46080
	ds_write_b128 v34, v[124:127] offset:13824
	s_waitcnt vmcnt(8)
	ds_write_b128 v34, v[128:131] offset:50688
	s_branch .LBB0_68

; #define LOADS(S, k0) { LD1(S, 0, k0) LD1(S, 1, k0) LD1(S, 2, k0) LD1(S, 3, k0) }
; #define STORES(S, buf) { ST1(S, 0, buf) ST1(S, 1, buf) ST1(S, 2, buf) ST1(S, 3, buf) }
; template <int AMODE, bool F16 = false, bool MASK = false>
; DI void gemm_tile(const bf16_t* __restrict__ Ab, int lda, int row0, int rlo, int rhi,
;                   const bf16_t* __restrict__ Bt, int ldb, int K, char* smem, f32x16 (&acc)[2][2]) {
;     ...
;     for (int kt = 0; kt < nk; kt += 2) {
;         COMPUTE(0);
;         STORES(p1, 1);
;         LOADS(p1, min((kt + 3) * 64, klast));
;         __syncthreads();
;         COMPUTE(1);
;         if (kt + 2 < nk) STORES(p0, 0);
;         LOADS(p0, min((kt + 4) * 64, klast));
;         __syncthreads();
.LBB0_74:
	s_min_u32 s15, s12, 0x2c0
	s_lshl_b32 s18, s15, 1
	s_add_i32 s56, s18, 0x200
	s_mov_b32 s19, s57
	s_mov_b64 s[100:101], exec
	s_cmp_gt_u32 s12, 0x2c0
	s_cselect_b64 exec, 1, s[100:101]
	v_lshl_add_u64 v[92:93], v[148:149], 0, s[56:57]
	v_lshl_add_u64 v[94:95], v[156:157], 0, s[18:19]
	v_lshl_add_u64 v[104:105], v[150:151], 0, s[56:57]
	v_lshl_add_u64 v[106:107], v[158:159], 0, s[18:19]
	global_load_dwordx4 v[112:115], v[92:93], off
	s_nop 0
	global_load_dwordx4 v[92:95], v[94:95], off offset:512
	s_nop 0
	global_load_dwordx4 v[116:119], v[104:105], off
	global_load_dwordx4 v[108:111], v[106:107], off offset:512
	v_lshl_add_u64 v[104:105], v[152:153], 0, s[56:57]
	v_lshl_add_u64 v[106:107], v[160:161], 0, s[18:19]
	v_lshl_add_u64 v[124:125], v[154:155], 0, s[56:57]
	s_waitcnt vmcnt(12)
	v_lshl_add_u64 v[128:129], v[162:163], 0, s[18:19]
	global_load_dwordx4 v[120:123], v[104:105], off
	s_nop 0
	global_load_dwordx4 v[104:107], v[106:107], off offset:512
	s_nop 0
	global_load_dwordx4 v[124:127], v[124:125], off
	s_nop 0
	global_load_dwordx4 v[128:131], v[128:129], off offset:512
	s_mov_b64 exec, s[100:101]
	s_add_i32 s13, s13, 2
	s_addk_i32 s12, 0x80
	s_and_b64 vcc, exec, s[16:17]
	s_waitcnt lgkmcnt(0)
	s_barrier
	s_cbranch_vccnz .LBB0_77

; #define LOADS(S, k0) { LD1(S, 0, k0) LD1(S, 1, k0) LD1(S, 2, k0) LD1(S, 3, k0) }
; #define STORES(S, buf) { ST1(S, 0, buf) ST1(S, 1, buf) ST1(S, 2, buf) ST1(S, 3, buf) }
; template <int AMODE, bool F16 = false, bool MASK = false>
; DI void gemm_tile(const bf16_t* __restrict__ Ab, int lda, int row0, int rlo, int rhi,
;                   const bf16_t* __restrict__ Bt, int ldb, int K, char* smem, f32x16 (&acc)[2][2]) {
;     ...
;     for (int kt = 0; kt < nk; kt += 2) {
;         COMPUTE(0);
;         STORES(p1, 1);
;         LOADS(p1, min((kt + 3) * 64, klast));
;         __syncthreads();
;         COMPUTE(1);
;         if (kt + 2 < nk) STORES(p0, 0);
;         LOADS(p0, min((kt + 4) * 64, klast));
;         __syncthreads();
.LBB0_95:
	s_min_u32 s34, s12, 0x2c0
	s_lshl_b32 s34, s34, 1
	s_add_i32 s56, s34, 0x200
	s_mov_b32 s35, s57
	s_mov_b64 s[100:101], exec
	s_cmp_gt_u32 s12, 0x2c0
	s_cselect_b64 exec, 1, s[100:101]
	v_lshl_add_u64 v[80:81], v[132:133], 0, s[56:57]
	v_lshl_add_u64 v[84:85], v[32:33], 0, s[34:35]
	v_lshl_add_u64 v[92:93], v[134:135], 0, s[56:57]
	global_load_dwordx4 v[80:83], v[80:81], off
	s_nop 0
	global_load_dwordx4 v[84:87], v[84:85], off offset:512
	v_lshl_add_u64 v[94:95], v[136:137], 0, s[34:35]
	global_load_dwordx4 v[104:107], v[92:93], off
	global_load_dwordx4 v[112:115], v[94:95], off offset:512
	v_lshl_add_u64 v[92:93], v[138:139], 0, s[56:57]
	v_lshl_add_u64 v[96:97], v[140:141], 0, s[34:35]
	v_lshl_add_u64 v[124:125], v[142:143], 0, s[56:57]
	s_waitcnt vmcnt(12)
	v_lshl_add_u64 v[128:129], v[144:145], 0, s[34:35]
	global_load_dwordx4 v[92:95], v[92:93], off
	s_nop 0
	global_load_dwordx4 v[96:99], v[96:97], off offset:512
	s_nop 0
	global_load_dwordx4 v[124:127], v[124:125], off
	s_nop 0
	global_load_dwordx4 v[128:131], v[128:129], off offset:512
	s_mov_b64 exec, s[100:101]
	s_add_i32 s13, s13, 2
	s_andn2_b64 vcc, exec, s[44:45]
	s_addk_i32 s12, 0x80
	s_waitcnt lgkmcnt(0)
	s_barrier
	s_cbranch_vccz .LBB0_98
; #define LOADS(S, k0) { LD1(S, 0, k0) LD1(S, 1, k0) LD1(S, 2, k0) LD1(S, 3, k0) }
; #define STORES(S, buf) { ST1(S, 0, buf) ST1(S, 1, buf) ST1(S, 2, buf) ST1(S, 3, buf) }
; template <int AMODE, bool F16 = false, bool MASK = false>
; DI void gemm_tile(const bf16_t* __restrict__ Ab, int lda, int row0, int rlo, int rhi,
;                   const bf16_t* __restrict__ Bt, int ldb, int K, char* smem, f32x16 (&acc)[2][2]) {
;     ...
;     for (int kt = 0; kt < nk; kt += 2) {
;         COMPUTE(0);
;         STORES(p1, 1);
;         LOADS(p1, min((kt + 3) * 64, klast));
;         __syncthreads();
;         COMPUTE(1);
;         if (kt + 2 < nk) STORES(p0, 0);
;         LOADS(p0, min((kt + 4) * 64, klast));
;         __syncthreads();
.LBB0_96:
	ds_read_b128 v[150:153], v34
	ds_read_b128 v[154:157], v34 offset:32
	ds_read_b128 v[158:161], v34 offset:4608
	ds_read_b128 v[162:165], v34 offset:4640
	ds_read_b128 v[166:169], v147 offset:36864
	ds_read_b128 v[170:173], v147 offset:36896
	ds_read_b128 v[174:177], v147 offset:41472
	ds_read_b128 v[178:181], v147 offset:41504
	s_setprio 1
	s_waitcnt lgkmcnt(3)
	v_mfma_f32_32x32x16_bf16 v[52:67], v[150:153], v[166:169], v[52:67]
	s_waitcnt lgkmcnt(1)
	v_mfma_f32_32x32x16_bf16 v[36:51], v[150:153], v[174:177], v[36:51]
	v_mfma_f32_32x32x16_bf16 v[16:31], v[158:161], v[166:169], v[16:31]
	v_mfma_f32_32x32x16_bf16 v[0:15], v[158:161], v[174:177], v[0:15]
	s_setprio 0
	ds_read_b128 v[150:153], v34 offset:64
	ds_read_b128 v[158:161], v34 offset:4672
	ds_read_b128 v[166:169], v147 offset:36928
	ds_read_b128 v[174:177], v147 offset:41536
	s_setprio 1
	v_mfma_f32_32x32x16_bf16 v[52:67], v[154:157], v[170:173], v[52:67]
	s_waitcnt lgkmcnt(4)
	v_mfma_f32_32x32x16_bf16 v[36:51], v[154:157], v[178:181], v[36:51]
	v_mfma_f32_32x32x16_bf16 v[16:31], v[162:165], v[170:173], v[16:31]
	v_mfma_f32_32x32x16_bf16 v[0:15], v[162:165], v[178:181], v[0:15]
	s_setprio 0
	ds_read_b128 v[154:157], v34 offset:96
	ds_read_b128 v[162:165], v34 offset:4704
	ds_read_b128 v[170:173], v147 offset:36960
	ds_read_b128 v[178:181], v147 offset:41568
	s_setprio 1
	s_waitcnt lgkmcnt(5)
	v_mfma_f32_32x32x16_bf16 v[52:67], v[150:153], v[166:169], v[52:67]
	s_waitcnt lgkmcnt(4)
	v_mfma_f32_32x32x16_bf16 v[36:51], v[150:153], v[174:177], v[36:51]
	v_mfma_f32_32x32x16_bf16 v[16:31], v[158:161], v[166:169], v[16:31]
	v_mfma_f32_32x32x16_bf16 v[0:15], v[158:161], v[174:177], v[0:15]
	s_setprio 0
	s_setprio 1
	s_waitcnt lgkmcnt(1)
	v_mfma_f32_32x32x16_bf16 v[52:67], v[154:157], v[170:173], v[52:67]
	s_waitcnt lgkmcnt(0)
	v_mfma_f32_32x32x16_bf16 v[36:51], v[154:157], v[178:181], v[36:51]
	v_mfma_f32_32x32x16_bf16 v[16:31], v[162:165], v[170:173], v[16:31]
	v_mfma_f32_32x32x16_bf16 v[0:15], v[162:165], v[178:181], v[0:15]
	s_setprio 0
	s_min_u32 s34, s12, 0x300
	s_lshl_b32 s34, s34, 1
	s_add_i32 s56, s34, 0x180
	s_mov_b32 s35, s57
	s_waitcnt vmcnt(15)
	ds_write_b128 v146, v[68:71] offset:18432
	s_waitcnt vmcnt(14)
	ds_write_b128 v146, v[72:75] offset:55296
	s_waitcnt vmcnt(7)
	ds_write_b128 v146, v[100:103] offset:23040
	s_waitcnt vmcnt(5)
	ds_write_b128 v146, v[108:111] offset:59904
	ds_write_b128 v146, v[76:79] offset:27648
	ds_write_b128 v146, v[88:91] offset:64512
	s_waitcnt vmcnt(3)
	ds_write_b128 v146, v[116:119] offset:32256
	s_waitcnt vmcnt(1)
	ds_write_b128 v148, v[120:123] offset:13824
	s_mov_b64 s[100:101], exec
	s_cmp_gt_u32 s12, 0x300
	s_cselect_b64 exec, 1, s[100:101]
	v_lshl_add_u64 v[68:69], v[132:133], 0, s[56:57]
	v_lshl_add_u64 v[72:73], v[32:33], 0, s[34:35]
	v_lshl_add_u64 v[76:77], v[134:135], 0, s[56:57]
	global_load_dwordx4 v[68:71], v[68:69], off
	s_nop 0
	global_load_dwordx4 v[72:75], v[72:73], off offset:384
	v_lshl_add_u64 v[78:79], v[136:137], 0, s[34:35]
	global_load_dwordx4 v[100:103], v[76:77], off
	global_load_dwordx4 v[108:111], v[78:79], off offset:384
	v_lshl_add_u64 v[76:77], v[138:139], 0, s[56:57]
	v_lshl_add_u64 v[88:89], v[140:141], 0, s[34:35]
	v_lshl_add_u64 v[116:117], v[142:143], 0, s[56:57]
	v_lshl_add_u64 v[120:121], v[144:145], 0, s[34:35]
	global_load_dwordx4 v[76:79], v[76:77], off
	s_nop 0
	global_load_dwordx4 v[88:91], v[88:89], off offset:384
	s_nop 0
	global_load_dwordx4 v[116:119], v[116:117], off
	s_nop 0
	global_load_dwordx4 v[120:123], v[120:121], off offset:384
	s_mov_b64 exec, s[100:101]
	s_waitcnt lgkmcnt(0)
	s_barrier
	ds_read_b128 v[150:153], v34 offset:18432
	ds_read_b128 v[154:157], v34 offset:18464
	ds_read_b128 v[158:161], v34 offset:23040
	ds_read_b128 v[162:165], v34 offset:23072
	ds_read_b128 v[166:169], v147 offset:55296
	ds_read_b128 v[170:173], v147 offset:55328
	ds_read_b128 v[174:177], v147 offset:59904
	ds_read_b128 v[178:181], v147 offset:59936
	s_setprio 1
	s_waitcnt lgkmcnt(3)
	v_mfma_f32_32x32x16_bf16 v[52:67], v[150:153], v[166:169], v[52:67]
	s_waitcnt lgkmcnt(1)
	v_mfma_f32_32x32x16_bf16 v[36:51], v[150:153], v[174:177], v[36:51]
	v_mfma_f32_32x32x16_bf16 v[16:31], v[158:161], v[166:169], v[16:31]
	v_mfma_f32_32x32x16_bf16 v[0:15], v[158:161], v[174:177], v[0:15]
	s_setprio 0
	ds_read_b128 v[150:153], v34 offset:18496
	ds_read_b128 v[158:161], v34 offset:23104
	ds_read_b128 v[166:169], v147 offset:55360
	ds_read_b128 v[174:177], v147 offset:59968
	s_setprio 1
	v_mfma_f32_32x32x16_bf16 v[52:67], v[154:157], v[170:173], v[52:67]
	s_waitcnt lgkmcnt(4)
	v_mfma_f32_32x32x16_bf16 v[36:51], v[154:157], v[178:181], v[36:51]
	v_mfma_f32_32x32x16_bf16 v[16:31], v[162:165], v[170:173], v[16:31]
	v_mfma_f32_32x32x16_bf16 v[0:15], v[162:165], v[178:181], v[0:15]
	s_setprio 0
	ds_read_b128 v[154:157], v34 offset:18528
	ds_read_b128 v[162:165], v34 offset:23136
	ds_read_b128 v[170:173], v147 offset:55392
	ds_read_b128 v[178:181], v147 offset:60000
	s_setprio 1
	s_waitcnt lgkmcnt(5)
	v_mfma_f32_32x32x16_bf16 v[52:67], v[150:153], v[166:169], v[52:67]
	s_waitcnt lgkmcnt(4)
	v_mfma_f32_32x32x16_bf16 v[36:51], v[150:153], v[174:177], v[36:51]
	v_mfma_f32_32x32x16_bf16 v[16:31], v[158:161], v[166:169], v[16:31]
	v_mfma_f32_32x32x16_bf16 v[0:15], v[158:161], v[174:177], v[0:15]
	s_setprio 0
	s_setprio 1
	s_waitcnt lgkmcnt(1)
	v_mfma_f32_32x32x16_bf16 v[52:67], v[154:157], v[170:173], v[52:67]
	s_waitcnt lgkmcnt(0)
	v_mfma_f32_32x32x16_bf16 v[36:51], v[154:157], v[178:181], v[36:51]
	v_mfma_f32_32x32x16_bf16 v[16:31], v[162:165], v[170:173], v[16:31]
	v_mfma_f32_32x32x16_bf16 v[0:15], v[162:165], v[178:181], v[0:15]
	s_setprio 0
	s_cmp_gt_u32 s13, 13
	s_cselect_b64 s[44:45], -1, 0
	s_and_b64 vcc, exec, s[44:45]
	s_cbranch_vccnz .LBB0_95
	ds_write_b128 v146, v[80:83]
	ds_write_b128 v146, v[84:87] offset:36864
	ds_write_b128 v146, v[104:107] offset:4608
	ds_write_b128 v146, v[112:115] offset:41472
	ds_write_b128 v146, v[92:95] offset:9216
	ds_write_b128 v146, v[96:99] offset:46080
	ds_write_b128 v146, v[124:127] offset:13824
	s_waitcnt vmcnt(8)
	ds_write_b128 v146, v[128:131] offset:50688
	s_branch .LBB0_95

; #define LOADS(S, k0) { LD1(S, 0, k0) LD1(S, 1, k0) LD1(S, 2, k0) LD1(S, 3, k0) }
; #define STORES(S, buf) { ST1(S, 0, buf) ST1(S, 1, buf) ST1(S, 2, buf) ST1(S, 3, buf) }
; template <int AMODE, bool F16 = false, bool MASK = false>
; DI void gemm_tile(const bf16_t* __restrict__ Ab, int lda, int row0, int rlo, int rhi,
;                   const bf16_t* __restrict__ Bt, int ldb, int K, char* smem, f32x16 (&acc)[2][2]) {
;     ...
;     for (int kt = 0; kt < nk; kt += 2) {
;         COMPUTE(0);
;         STORES(p1, 1);
;         LOADS(p1, min((kt + 3) * 64, klast));
;         __syncthreads();
;         COMPUTE(1);
;         if (kt + 2 < nk) STORES(p0, 0);
;         LOADS(p0, min((kt + 4) * 64, klast));
;         __syncthreads();
.LBB0_142:
	s_min_u32 s9, s7, 0x2c0
	s_lshl_b32 s10, s9, 1
	s_add_i32 s56, s10, 0x200
	s_mov_b32 s11, s57
	s_mov_b64 s[100:101], exec
	s_cmp_gt_u32 s7, 0x2c0
	s_cselect_b64 exec, 1, s[100:101]
	v_lshl_add_u64 v[84:85], v[32:33], 0, s[56:57]
	v_lshl_add_u64 v[88:89], v[138:139], 0, s[10:11]
	global_load_dwordx4 v[84:87], v[84:85], off
	s_nop 0
	global_load_dwordx4 v[100:103], v[88:89], off offset:512
	v_lshl_add_u64 v[88:89], v[132:133], 0, s[56:57]
	v_lshl_add_u64 v[90:91], v[140:141], 0, s[10:11]
	global_load_dwordx4 v[108:111], v[88:89], off
	global_load_dwordx4 v[92:95], v[90:91], off offset:512
	v_lshl_add_u64 v[88:89], v[134:135], 0, s[56:57]
	s_waitcnt vmcnt(12)
	v_lshl_add_u64 v[112:113], v[142:143], 0, s[10:11]
	global_load_dwordx4 v[88:91], v[88:89], off
	s_nop 0
	global_load_dwordx4 v[120:123], v[112:113], off offset:512
	v_lshl_add_u64 v[112:113], v[136:137], 0, s[56:57]
	v_lshl_add_u64 v[114:115], v[144:145], 0, s[10:11]
	global_load_dwordx4 v[128:131], v[112:113], off
	s_nop 0
	global_load_dwordx4 v[112:115], v[114:115], off offset:512
	s_mov_b64 exec, s[100:101]
	s_add_i32 s8, s8, 2
	s_andn2_b64 vcc, exec, s[18:19]
	s_addk_i32 s7, 0x80
	s_waitcnt lgkmcnt(0)
	s_barrier
	s_cbranch_vccz .LBB0_145
; #define LOADS(S, k0) { LD1(S, 0, k0) LD1(S, 1, k0) LD1(S, 2, k0) LD1(S, 3, k0) }
; #define STORES(S, buf) { ST1(S, 0, buf) ST1(S, 1, buf) ST1(S, 2, buf) ST1(S, 3, buf) }
; template <int AMODE, bool F16 = false, bool MASK = false>
; DI void gemm_tile(const bf16_t* __restrict__ Ab, int lda, int row0, int rlo, int rhi,
;                   const bf16_t* __restrict__ Bt, int ldb, int K, char* smem, f32x16 (&acc)[2][2]) {
;     ...
;     for (int kt = 0; kt < nk; kt += 2) {
;         COMPUTE(0);
;         STORES(p1, 1);
;         LOADS(p1, min((kt + 3) * 64, klast));
;         __syncthreads();
;         COMPUTE(1);
;         if (kt + 2 < nk) STORES(p0, 0);
;         LOADS(p0, min((kt + 4) * 64, klast));
;         __syncthreads();
.LBB0_143:
	ds_read_b128 v[150:153], v34
	ds_read_b128 v[154:157], v34 offset:32
	ds_read_b128 v[158:161], v34 offset:4608
	ds_read_b128 v[162:165], v34 offset:4640
	ds_read_b128 v[166:169], v148 offset:36864
	ds_read_b128 v[170:173], v148 offset:36896
	ds_read_b128 v[174:177], v148 offset:41472
	ds_read_b128 v[178:181], v148 offset:41504
	s_setprio 1
	s_waitcnt lgkmcnt(3)
	v_mfma_f32_32x32x16_f16 v[36:51], v[150:153], v[166:169], v[36:51]
	s_waitcnt lgkmcnt(1)
	v_mfma_f32_32x32x16_f16 v[52:67], v[150:153], v[174:177], v[52:67]
	v_mfma_f32_32x32x16_f16 v[16:31], v[158:161], v[166:169], v[16:31]
	v_mfma_f32_32x32x16_f16 v[0:15], v[158:161], v[174:177], v[0:15]
	s_setprio 0
	ds_read_b128 v[150:153], v34 offset:64
	ds_read_b128 v[158:161], v34 offset:4672
	ds_read_b128 v[166:169], v148 offset:36928
	ds_read_b128 v[174:177], v148 offset:41536
	s_setprio 1
	v_mfma_f32_32x32x16_f16 v[36:51], v[154:157], v[170:173], v[36:51]
	s_waitcnt lgkmcnt(4)
	v_mfma_f32_32x32x16_f16 v[52:67], v[154:157], v[178:181], v[52:67]
	v_mfma_f32_32x32x16_f16 v[16:31], v[162:165], v[170:173], v[16:31]
	v_mfma_f32_32x32x16_f16 v[0:15], v[162:165], v[178:181], v[0:15]
	s_setprio 0
	ds_read_b128 v[154:157], v34 offset:96
	ds_read_b128 v[162:165], v34 offset:4704
	ds_read_b128 v[170:173], v148 offset:36960
	ds_read_b128 v[178:181], v148 offset:41568
	s_setprio 1
	s_waitcnt lgkmcnt(5)
	v_mfma_f32_32x32x16_f16 v[36:51], v[150:153], v[166:169], v[36:51]
	s_waitcnt lgkmcnt(4)
	v_mfma_f32_32x32x16_f16 v[52:67], v[150:153], v[174:177], v[52:67]
	v_mfma_f32_32x32x16_f16 v[16:31], v[158:161], v[166:169], v[16:31]
	v_mfma_f32_32x32x16_f16 v[0:15], v[158:161], v[174:177], v[0:15]
	s_setprio 0
	s_setprio 1
	s_waitcnt lgkmcnt(1)
	v_mfma_f32_32x32x16_f16 v[36:51], v[154:157], v[170:173], v[36:51]
	s_waitcnt lgkmcnt(0)
	v_mfma_f32_32x32x16_f16 v[52:67], v[154:157], v[178:181], v[52:67]
	v_mfma_f32_32x32x16_f16 v[16:31], v[162:165], v[170:173], v[16:31]
	v_mfma_f32_32x32x16_f16 v[0:15], v[162:165], v[178:181], v[0:15]
	s_setprio 0
	s_min_u32 s9, s7, 0x300
	s_lshl_b32 s10, s9, 1
	s_add_i32 s56, s10, 0x180
	s_mov_b32 s11, s57
	s_waitcnt vmcnt(15)
	ds_write_b128 v147, v[68:71] offset:18432
	s_waitcnt vmcnt(7)
	ds_write_b128 v147, v[96:99] offset:55296
	s_waitcnt vmcnt(5)
	ds_write_b128 v147, v[104:107] offset:23040
	ds_write_b128 v147, v[72:75] offset:59904
	ds_write_b128 v147, v[76:79] offset:27648
	s_waitcnt vmcnt(3)
	ds_write_b128 v147, v[116:119] offset:64512
	s_waitcnt vmcnt(1)
	ds_write_b128 v147, v[124:127] offset:32256
	ds_write_b128 v149, v[80:83] offset:13824
	s_mov_b64 s[100:101], exec
	s_cmp_gt_u32 s7, 0x300
	s_cselect_b64 exec, 1, s[100:101]
	v_lshl_add_u64 v[68:69], v[32:33], 0, s[56:57]
	v_lshl_add_u64 v[72:73], v[138:139], 0, s[10:11]
	global_load_dwordx4 v[68:71], v[68:69], off
	s_nop 0
	global_load_dwordx4 v[96:99], v[72:73], off offset:384
	v_lshl_add_u64 v[72:73], v[132:133], 0, s[56:57]
	v_lshl_add_u64 v[74:75], v[140:141], 0, s[10:11]
	v_lshl_add_u64 v[76:77], v[134:135], 0, s[56:57]
	v_lshl_add_u64 v[80:81], v[142:143], 0, s[10:11]
	global_load_dwordx4 v[104:107], v[72:73], off
	s_nop 0
	global_load_dwordx4 v[72:75], v[74:75], off offset:384
	s_nop 0
	global_load_dwordx4 v[76:79], v[76:77], off
	s_nop 0
	global_load_dwordx4 v[116:119], v[80:81], off offset:384
	v_lshl_add_u64 v[80:81], v[136:137], 0, s[56:57]
	v_lshl_add_u64 v[82:83], v[144:145], 0, s[10:11]
	global_load_dwordx4 v[124:127], v[80:81], off
	s_nop 0
	global_load_dwordx4 v[80:83], v[82:83], off offset:384
	s_mov_b64 exec, s[100:101]
	s_waitcnt lgkmcnt(0)
	s_barrier
	ds_read_b128 v[150:153], v34 offset:18432
	ds_read_b128 v[154:157], v34 offset:18464
	ds_read_b128 v[158:161], v34 offset:23040
	ds_read_b128 v[162:165], v34 offset:23072
	ds_read_b128 v[166:169], v148 offset:55296
	ds_read_b128 v[170:173], v148 offset:55328
	ds_read_b128 v[174:177], v148 offset:59904
	ds_read_b128 v[178:181], v148 offset:59936
	s_setprio 1
	s_waitcnt lgkmcnt(3)
	v_mfma_f32_32x32x16_f16 v[36:51], v[150:153], v[166:169], v[36:51]
	s_waitcnt lgkmcnt(1)
	v_mfma_f32_32x32x16_f16 v[52:67], v[150:153], v[174:177], v[52:67]
	v_mfma_f32_32x32x16_f16 v[16:31], v[158:161], v[166:169], v[16:31]
	v_mfma_f32_32x32x16_f16 v[0:15], v[158:161], v[174:177], v[0:15]
	s_setprio 0
	ds_read_b128 v[150:153], v34 offset:18496
	ds_read_b128 v[158:161], v34 offset:23104
	ds_read_b128 v[166:169], v148 offset:55360
	ds_read_b128 v[174:177], v148 offset:59968
	s_setprio 1
	v_mfma_f32_32x32x16_f16 v[36:51], v[154:157], v[170:173], v[36:51]
	s_waitcnt lgkmcnt(4)
	v_mfma_f32_32x32x16_f16 v[52:67], v[154:157], v[178:181], v[52:67]
	v_mfma_f32_32x32x16_f16 v[16:31], v[162:165], v[170:173], v[16:31]
	v_mfma_f32_32x32x16_f16 v[0:15], v[162:165], v[178:181], v[0:15]
	s_setprio 0
	ds_read_b128 v[154:157], v34 offset:18528
	ds_read_b128 v[162:165], v34 offset:23136
	ds_read_b128 v[170:173], v148 offset:55392
	ds_read_b128 v[178:181], v148 offset:60000
	s_setprio 1
	s_waitcnt lgkmcnt(5)
	v_mfma_f32_32x32x16_f16 v[36:51], v[150:153], v[166:169], v[36:51]
	s_waitcnt lgkmcnt(4)
	v_mfma_f32_32x32x16_f16 v[52:67], v[150:153], v[174:177], v[52:67]
	v_mfma_f32_32x32x16_f16 v[16:31], v[158:161], v[166:169], v[16:31]
	v_mfma_f32_32x32x16_f16 v[0:15], v[158:161], v[174:177], v[0:15]
	s_setprio 0
	s_setprio 1
	s_waitcnt lgkmcnt(1)
	v_mfma_f32_32x32x16_f16 v[36:51], v[154:157], v[170:173], v[36:51]
	s_waitcnt lgkmcnt(0)
	v_mfma_f32_32x32x16_f16 v[52:67], v[154:157], v[178:181], v[52:67]
	v_mfma_f32_32x32x16_f16 v[16:31], v[162:165], v[170:173], v[16:31]
	v_mfma_f32_32x32x16_f16 v[0:15], v[162:165], v[178:181], v[0:15]
	s_setprio 0
	s_cmp_gt_u32 s8, 13
	s_cselect_b64 s[18:19], -1, 0
	s_and_b64 vcc, exec, s[18:19]
	s_cbranch_vccnz .LBB0_142
	ds_write_b128 v147, v[84:87]
	ds_write_b128 v147, v[100:103] offset:36864
	ds_write_b128 v147, v[108:111] offset:4608
	ds_write_b128 v147, v[92:95] offset:41472
	ds_write_b128 v147, v[88:91] offset:9216
	ds_write_b128 v147, v[120:123] offset:46080
	s_waitcnt vmcnt(8)
	ds_write_b128 v147, v[128:131] offset:13824
	ds_write_b128 v147, v[112:115] offset:50688
	s_branch .LBB0_142

; #define LOADS(S, k0) { LD1(S, 0, k0) LD1(S, 1, k0) LD1(S, 2, k0) LD1(S, 3, k0) }
; #define STORES(S, buf) { ST1(S, 0, buf) ST1(S, 1, buf) ST1(S, 2, buf) ST1(S, 3, buf) }
; template <int AMODE, bool F16 = false, bool MASK = false>
; DI void gemm_tile(const bf16_t* __restrict__ Ab, int lda, int row0, int rlo, int rhi,
;                   const bf16_t* __restrict__ Bt, int ldb, int K, char* smem, f32x16 (&acc)[2][2]) {
;     ...
;     for (int kt = 0; kt < nk; kt += 2) {
;         COMPUTE(0);
;         STORES(p1, 1);
;         LOADS(p1, min((kt + 3) * 64, klast));
;         __syncthreads();
;         COMPUTE(1);
;         if (kt + 2 < nk) STORES(p0, 0);
;         LOADS(p0, min((kt + 4) * 64, klast));
;         __syncthreads();
.LBB0_151:
	s_min_u32 s34, s12, 0x2c0
	s_lshl_b32 s34, s34, 1
	s_add_i32 s56, s34, 0x200
	s_mov_b32 s35, s57
	s_mov_b64 s[100:101], exec
	s_cmp_gt_u32 s12, 0x2c0
	s_cselect_b64 exec, 1, s[100:101]
	v_lshl_add_u64 v[72:73], v[132:133], 0, s[56:57]
	v_lshl_add_u64 v[74:75], v[32:33], 0, s[34:35]
	v_lshl_add_u64 v[84:85], v[134:135], 0, s[56:57]
	global_load_dwordx4 v[104:107], v[72:73], off
	s_nop 0
	global_load_dwordx4 v[72:75], v[74:75], off offset:512
	v_lshl_add_u64 v[86:87], v[136:137], 0, s[34:35]
	global_load_dwordx4 v[112:115], v[84:85], off
	global_load_dwordx4 v[88:91], v[86:87], off offset:512
	v_lshl_add_u64 v[84:85], v[138:139], 0, s[56:57]
	s_waitcnt vmcnt(12)
	v_lshl_add_u64 v[96:97], v[140:141], 0, s[34:35]
	global_load_dwordx4 v[84:87], v[84:85], off
	s_nop 0
	global_load_dwordx4 v[120:123], v[96:97], off offset:512
	v_lshl_add_u64 v[96:97], v[142:143], 0, s[56:57]
	v_lshl_add_u64 v[98:99], v[144:145], 0, s[34:35]
	global_load_dwordx4 v[128:131], v[96:97], off
	s_nop 0
	global_load_dwordx4 v[96:99], v[98:99], off offset:512
	s_mov_b64 exec, s[100:101]
	s_add_i32 s13, s13, 2
	s_andn2_b64 vcc, exec, s[44:45]
	s_addk_i32 s12, 0x80
	s_waitcnt lgkmcnt(0)
	s_barrier
	s_cbranch_vccz .LBB0_154
; #define LOADS(S, k0) { LD1(S, 0, k0) LD1(S, 1, k0) LD1(S, 2, k0) LD1(S, 3, k0) }
; #define STORES(S, buf) { ST1(S, 0, buf) ST1(S, 1, buf) ST1(S, 2, buf) ST1(S, 3, buf) }
; template <int AMODE, bool F16 = false, bool MASK = false>
; DI void gemm_tile(const bf16_t* __restrict__ Ab, int lda, int row0, int rlo, int rhi,
;                   const bf16_t* __restrict__ Bt, int ldb, int K, char* smem, f32x16 (&acc)[2][2]) {
;     ...
;     for (int kt = 0; kt < nk; kt += 2) {
;         COMPUTE(0);
;         STORES(p1, 1);
;         LOADS(p1, min((kt + 3) * 64, klast));
;         __syncthreads();
;         COMPUTE(1);
;         if (kt + 2 < nk) STORES(p0, 0);
;         LOADS(p0, min((kt + 4) * 64, klast));
;         __syncthreads();
.LBB0_152:
	ds_read_b128 v[150:153], v34
	ds_read_b128 v[154:157], v34 offset:32
	ds_read_b128 v[158:161], v34 offset:4608
	ds_read_b128 v[162:165], v34 offset:4640
	ds_read_b128 v[166:169], v147 offset:36864
	ds_read_b128 v[170:173], v147 offset:36896
	ds_read_b128 v[174:177], v147 offset:41472
	ds_read_b128 v[178:181], v147 offset:41504
	s_setprio 1
	s_waitcnt lgkmcnt(3)
	v_mfma_f32_32x32x16_bf16 v[52:67], v[150:153], v[166:169], v[52:67]
	s_waitcnt lgkmcnt(1)
	v_mfma_f32_32x32x16_bf16 v[36:51], v[150:153], v[174:177], v[36:51]
	v_mfma_f32_32x32x16_bf16 v[16:31], v[158:161], v[166:169], v[16:31]
	v_mfma_f32_32x32x16_bf16 v[0:15], v[158:161], v[174:177], v[0:15]
	s_setprio 0
	ds_read_b128 v[150:153], v34 offset:64
	ds_read_b128 v[158:161], v34 offset:4672
	ds_read_b128 v[166:169], v147 offset:36928
	ds_read_b128 v[174:177], v147 offset:41536
	s_setprio 1
	v_mfma_f32_32x32x16_bf16 v[52:67], v[154:157], v[170:173], v[52:67]
	s_waitcnt lgkmcnt(4)
	v_mfma_f32_32x32x16_bf16 v[36:51], v[154:157], v[178:181], v[36:51]
	v_mfma_f32_32x32x16_bf16 v[16:31], v[162:165], v[170:173], v[16:31]
	v_mfma_f32_32x32x16_bf16 v[0:15], v[162:165], v[178:181], v[0:15]
	s_setprio 0
	ds_read_b128 v[154:157], v34 offset:96
	ds_read_b128 v[162:165], v34 offset:4704
	ds_read_b128 v[170:173], v147 offset:36960
	ds_read_b128 v[178:181], v147 offset:41568
	s_setprio 1
	s_waitcnt lgkmcnt(5)
	v_mfma_f32_32x32x16_bf16 v[52:67], v[150:153], v[166:169], v[52:67]
	s_waitcnt lgkmcnt(4)
	v_mfma_f32_32x32x16_bf16 v[36:51], v[150:153], v[174:177], v[36:51]
	v_mfma_f32_32x32x16_bf16 v[16:31], v[158:161], v[166:169], v[16:31]
	v_mfma_f32_32x32x16_bf16 v[0:15], v[158:161], v[174:177], v[0:15]
	s_setprio 0
	s_setprio 1
	s_waitcnt lgkmcnt(1)
	v_mfma_f32_32x32x16_bf16 v[52:67], v[154:157], v[170:173], v[52:67]
	s_waitcnt lgkmcnt(0)
	v_mfma_f32_32x32x16_bf16 v[36:51], v[154:157], v[178:181], v[36:51]
	v_mfma_f32_32x32x16_bf16 v[16:31], v[162:165], v[170:173], v[16:31]
	v_mfma_f32_32x32x16_bf16 v[0:15], v[162:165], v[178:181], v[0:15]
	s_setprio 0
	s_min_u32 s34, s12, 0x300
	s_lshl_b32 s34, s34, 1
	s_add_i32 s56, s34, 0x180
	s_mov_b32 s35, s57
	s_waitcnt vmcnt(7)
	ds_write_b128 v146, v[100:103] offset:18432
	ds_write_b128 v146, v[68:71] offset:55296
	s_waitcnt vmcnt(5)
	ds_write_b128 v146, v[108:111] offset:23040
	ds_write_b128 v146, v[80:83] offset:59904
	ds_write_b128 v146, v[76:79] offset:27648
	s_waitcnt vmcnt(3)
	ds_write_b128 v146, v[116:119] offset:64512
	s_waitcnt vmcnt(1)
	ds_write_b128 v146, v[124:127] offset:32256
	ds_write_b128 v148, v[92:95] offset:13824
	s_mov_b64 s[100:101], exec
	s_cmp_gt_u32 s12, 0x300
	s_cselect_b64 exec, 1, s[100:101]
	v_lshl_add_u64 v[68:69], v[132:133], 0, s[56:57]
	v_lshl_add_u64 v[70:71], v[32:33], 0, s[34:35]
	v_lshl_add_u64 v[76:77], v[134:135], 0, s[56:57]
	global_load_dwordx4 v[100:103], v[68:69], off
	s_nop 0
	global_load_dwordx4 v[68:71], v[70:71], off offset:384
	v_lshl_add_u64 v[78:79], v[136:137], 0, s[34:35]
	global_load_dwordx4 v[108:111], v[76:77], off
	global_load_dwordx4 v[80:83], v[78:79], off offset:384
	v_lshl_add_u64 v[76:77], v[138:139], 0, s[56:57]
	v_lshl_add_u64 v[92:93], v[140:141], 0, s[34:35]
	global_load_dwordx4 v[76:79], v[76:77], off
	s_nop 0
	global_load_dwordx4 v[116:119], v[92:93], off offset:384
	v_lshl_add_u64 v[92:93], v[142:143], 0, s[56:57]
	v_lshl_add_u64 v[94:95], v[144:145], 0, s[34:35]
	global_load_dwordx4 v[124:127], v[92:93], off
	s_nop 0
	global_load_dwordx4 v[92:95], v[94:95], off offset:384
	s_mov_b64 exec, s[100:101]
	s_waitcnt lgkmcnt(0)
	s_barrier
	ds_read_b128 v[150:153], v34 offset:18432
	ds_read_b128 v[154:157], v34 offset:18464
	ds_read_b128 v[158:161], v34 offset:23040
	ds_read_b128 v[162:165], v34 offset:23072
	ds_read_b128 v[166:169], v147 offset:55296
	ds_read_b128 v[170:173], v147 offset:55328
	ds_read_b128 v[174:177], v147 offset:59904
	ds_read_b128 v[178:181], v147 offset:59936
	s_setprio 1
	s_waitcnt lgkmcnt(3)
	v_mfma_f32_32x32x16_bf16 v[52:67], v[150:153], v[166:169], v[52:67]
	s_waitcnt lgkmcnt(1)
	v_mfma_f32_32x32x16_bf16 v[36:51], v[150:153], v[174:177], v[36:51]
	v_mfma_f32_32x32x16_bf16 v[16:31], v[158:161], v[166:169], v[16:31]
	v_mfma_f32_32x32x16_bf16 v[0:15], v[158:161], v[174:177], v[0:15]
	s_setprio 0
	ds_read_b128 v[150:153], v34 offset:18496
	ds_read_b128 v[158:161], v34 offset:23104
	ds_read_b128 v[166:169], v147 offset:55360
	ds_read_b128 v[174:177], v147 offset:59968
	s_setprio 1
	v_mfma_f32_32x32x16_bf16 v[52:67], v[154:157], v[170:173], v[52:67]
	s_waitcnt lgkmcnt(4)
	v_mfma_f32_32x32x16_bf16 v[36:51], v[154:157], v[178:181], v[36:51]
	v_mfma_f32_32x32x16_bf16 v[16:31], v[162:165], v[170:173], v[16:31]
	v_mfma_f32_32x32x16_bf16 v[0:15], v[162:165], v[178:181], v[0:15]
	s_setprio 0
	ds_read_b128 v[154:157], v34 offset:18528
	ds_read_b128 v[162:165], v34 offset:23136
	ds_read_b128 v[170:173], v147 offset:55392
	ds_read_b128 v[178:181], v147 offset:60000
	s_setprio 1
	s_waitcnt lgkmcnt(5)
	v_mfma_f32_32x32x16_bf16 v[52:67], v[150:153], v[166:169], v[52:67]
	s_waitcnt lgkmcnt(4)
	v_mfma_f32_32x32x16_bf16 v[36:51], v[150:153], v[174:177], v[36:51]
	v_mfma_f32_32x32x16_bf16 v[16:31], v[158:161], v[166:169], v[16:31]
	v_mfma_f32_32x32x16_bf16 v[0:15], v[158:161], v[174:177], v[0:15]
	s_setprio 0
	s_setprio 1
	s_waitcnt lgkmcnt(1)
	v_mfma_f32_32x32x16_bf16 v[52:67], v[154:157], v[170:173], v[52:67]
	s_waitcnt lgkmcnt(0)
	v_mfma_f32_32x32x16_bf16 v[36:51], v[154:157], v[178:181], v[36:51]
	v_mfma_f32_32x32x16_bf16 v[16:31], v[162:165], v[170:173], v[16:31]
	v_mfma_f32_32x32x16_bf16 v[0:15], v[162:165], v[178:181], v[0:15]
	s_setprio 0
	s_cmp_gt_u32 s13, 13
	s_cselect_b64 s[44:45], -1, 0
	s_and_b64 vcc, exec, s[44:45]
	s_cbranch_vccnz .LBB0_151
	ds_write_b128 v146, v[104:107]
	ds_write_b128 v146, v[72:75] offset:36864
	ds_write_b128 v146, v[112:115] offset:4608
	ds_write_b128 v146, v[88:91] offset:41472
	ds_write_b128 v146, v[84:87] offset:9216
	ds_write_b128 v146, v[120:123] offset:46080
	s_waitcnt vmcnt(8)
	ds_write_b128 v146, v[128:131] offset:13824
	ds_write_b128 v146, v[96:99] offset:50688
	s_branch .LBB0_151

; #define LOADS(S, k0) { LD1(S, 0, k0) LD1(S, 1, k0) LD1(S, 2, k0) LD1(S, 3, k0) }
; #define STORES(S, buf) { ST1(S, 0, buf) ST1(S, 1, buf) ST1(S, 2, buf) ST1(S, 3, buf) }
; template <int AMODE, bool F16 = false, bool MASK = false>
; DI void gemm_tile(const bf16_t* __restrict__ Ab, int lda, int row0, int rlo, int rhi,
;                   const bf16_t* __restrict__ Bt, int ldb, int K, char* smem, f32x16 (&acc)[2][2]) {
;     ...
;     for (int kt = 0; kt < nk; kt += 2) {
;         COMPUTE(0);
;         STORES(p1, 1);
;         LOADS(p1, min((kt + 3) * 64, klast));
;         __syncthreads();
;         COMPUTE(1);
;         if (kt + 2 < nk) STORES(p0, 0);
;         LOADS(p0, min((kt + 4) * 64, klast));
;         __syncthreads();
.LBB0_239:
	s_min_u32 s13, s11, 0x2c0
	s_lshl_b32 s16, s13, 1
	s_add_i32 s56, s16, 0x200
	s_mov_b32 s17, s57
	s_mov_b64 s[100:101], exec
	s_cmp_gt_u32 s11, 0x2c0
	s_cselect_b64 exec, 1, s[100:101]
	v_lshl_add_u64 v[72:73], v[132:133], 0, s[56:57]
	v_lshl_add_u64 v[74:75], v[32:33], 0, s[16:17]
	v_lshl_add_u64 v[84:85], v[134:135], 0, s[56:57]
	v_lshl_add_u64 v[86:87], v[140:141], 0, s[16:17]
	v_lshl_add_u64 v[92:93], v[136:137], 0, s[56:57]
	s_waitcnt vmcnt(8)
	v_lshl_add_u64 v[96:97], v[142:143], 0, s[16:17]
	global_load_dwordx4 v[104:107], v[72:73], off
	s_nop 0
	global_load_dwordx4 v[72:75], v[74:75], off offset:512
	s_nop 0
	global_load_dwordx4 v[112:115], v[84:85], off
	s_nop 0
	global_load_dwordx4 v[84:87], v[86:87], off offset:512
	s_nop 0
	global_load_dwordx4 v[92:95], v[92:93], off
	s_nop 0
	global_load_dwordx4 v[120:123], v[96:97], off offset:512
	v_lshl_add_u64 v[96:97], v[138:139], 0, s[56:57]
	v_lshl_add_u64 v[98:99], v[144:145], 0, s[16:17]
	global_load_dwordx4 v[128:131], v[96:97], off
	s_nop 0
	global_load_dwordx4 v[96:99], v[98:99], off offset:512
	s_mov_b64 exec, s[100:101]
	s_add_i32 s12, s12, 2
	s_andn2_b64 vcc, exec, s[14:15]
	s_addk_i32 s11, 0x80
	s_waitcnt lgkmcnt(0)
	s_barrier
	s_cbranch_vccz .LBB0_242
; #define LOADS(S, k0) { LD1(S, 0, k0) LD1(S, 1, k0) LD1(S, 2, k0) LD1(S, 3, k0) }
; #define STORES(S, buf) { ST1(S, 0, buf) ST1(S, 1, buf) ST1(S, 2, buf) ST1(S, 3, buf) }
; template <int AMODE, bool F16 = false, bool MASK = false>
; DI void gemm_tile(const bf16_t* __restrict__ Ab, int lda, int row0, int rlo, int rhi,
;                   const bf16_t* __restrict__ Bt, int ldb, int K, char* smem, f32x16 (&acc)[2][2]) {
;     ...
;     for (int kt = 0; kt < nk; kt += 2) {
;         COMPUTE(0);
;         STORES(p1, 1);
;         LOADS(p1, min((kt + 3) * 64, klast));
;         __syncthreads();
;         COMPUTE(1);
;         if (kt + 2 < nk) STORES(p0, 0);
;         LOADS(p0, min((kt + 4) * 64, klast));
;         __syncthreads();
.LBB0_240:
	ds_read_b128 v[150:153], v34
	ds_read_b128 v[154:157], v34 offset:32
	ds_read_b128 v[158:161], v34 offset:4608
	ds_read_b128 v[162:165], v34 offset:4640
	ds_read_b128 v[166:169], v148 offset:36864
	ds_read_b128 v[170:173], v148 offset:36896
	ds_read_b128 v[174:177], v148 offset:41472
	ds_read_b128 v[178:181], v148 offset:41504
	s_setprio 1
	s_waitcnt lgkmcnt(3)
	v_mfma_f32_32x32x16_f16 v[0:15], v[150:153], v[166:169], v[0:15]
	s_waitcnt lgkmcnt(1)
	v_mfma_f32_32x32x16_f16 v[52:67], v[150:153], v[174:177], v[52:67]
	v_mfma_f32_32x32x16_f16 v[36:51], v[158:161], v[166:169], v[36:51]
	v_mfma_f32_32x32x16_f16 v[16:31], v[158:161], v[174:177], v[16:31]
	s_setprio 0
	ds_read_b128 v[150:153], v34 offset:64
	ds_read_b128 v[158:161], v34 offset:4672
	ds_read_b128 v[166:169], v148 offset:36928
	ds_read_b128 v[174:177], v148 offset:41536
	s_setprio 1
	v_mfma_f32_32x32x16_f16 v[0:15], v[154:157], v[170:173], v[0:15]
	s_waitcnt lgkmcnt(4)
	v_mfma_f32_32x32x16_f16 v[52:67], v[154:157], v[178:181], v[52:67]
	v_mfma_f32_32x32x16_f16 v[36:51], v[162:165], v[170:173], v[36:51]
	v_mfma_f32_32x32x16_f16 v[16:31], v[162:165], v[178:181], v[16:31]
	s_setprio 0
	ds_read_b128 v[154:157], v34 offset:96
	ds_read_b128 v[162:165], v34 offset:4704
	ds_read_b128 v[170:173], v148 offset:36960
	ds_read_b128 v[178:181], v148 offset:41568
	s_setprio 1
	s_waitcnt lgkmcnt(5)
	v_mfma_f32_32x32x16_f16 v[0:15], v[150:153], v[166:169], v[0:15]
	s_waitcnt lgkmcnt(4)
	v_mfma_f32_32x32x16_f16 v[52:67], v[150:153], v[174:177], v[52:67]
	v_mfma_f32_32x32x16_f16 v[36:51], v[158:161], v[166:169], v[36:51]
	v_mfma_f32_32x32x16_f16 v[16:31], v[158:161], v[174:177], v[16:31]
	s_setprio 0
	s_setprio 1
	s_waitcnt lgkmcnt(1)
	v_mfma_f32_32x32x16_f16 v[0:15], v[154:157], v[170:173], v[0:15]
	s_waitcnt lgkmcnt(0)
	v_mfma_f32_32x32x16_f16 v[52:67], v[154:157], v[178:181], v[52:67]
	v_mfma_f32_32x32x16_f16 v[36:51], v[162:165], v[170:173], v[36:51]
	v_mfma_f32_32x32x16_f16 v[16:31], v[162:165], v[178:181], v[16:31]
	s_setprio 0
	s_min_u32 s13, s11, 0x300
	s_lshl_b32 s14, s13, 1
	s_add_i32 s56, s14, 0x180
	s_mov_b32 s15, s57
	s_waitcnt vmcnt(7)
	ds_write_b128 v147, v[100:103] offset:18432
	ds_write_b128 v147, v[68:71] offset:55296
	s_waitcnt vmcnt(5)
	ds_write_b128 v147, v[108:111] offset:23040
	ds_write_b128 v147, v[76:79] offset:59904
	ds_write_b128 v147, v[80:83] offset:27648
	s_waitcnt vmcnt(3)
	ds_write_b128 v147, v[116:119] offset:64512
	s_waitcnt vmcnt(1)
	ds_write_b128 v147, v[124:127] offset:32256
	ds_write_b128 v149, v[88:91] offset:13824
	s_mov_b64 s[100:101], exec
	s_cmp_gt_u32 s11, 0x300
	s_cselect_b64 exec, 1, s[100:101]
	v_lshl_add_u64 v[68:69], v[132:133], 0, s[56:57]
	v_lshl_add_u64 v[70:71], v[32:33], 0, s[14:15]
	v_lshl_add_u64 v[76:77], v[134:135], 0, s[56:57]
	v_lshl_add_u64 v[78:79], v[140:141], 0, s[14:15]
	v_lshl_add_u64 v[80:81], v[136:137], 0, s[56:57]
	v_lshl_add_u64 v[88:89], v[142:143], 0, s[14:15]
	global_load_dwordx4 v[100:103], v[68:69], off
	s_nop 0
	global_load_dwordx4 v[68:71], v[70:71], off offset:384
	s_nop 0
	global_load_dwordx4 v[108:111], v[76:77], off
	s_nop 0
	global_load_dwordx4 v[76:79], v[78:79], off offset:384
	s_nop 0
	global_load_dwordx4 v[80:83], v[80:81], off
	s_nop 0
	global_load_dwordx4 v[116:119], v[88:89], off offset:384
	v_lshl_add_u64 v[88:89], v[138:139], 0, s[56:57]
	v_lshl_add_u64 v[90:91], v[144:145], 0, s[14:15]
	global_load_dwordx4 v[124:127], v[88:89], off
	s_nop 0
	global_load_dwordx4 v[88:91], v[90:91], off offset:384
	s_mov_b64 exec, s[100:101]
	s_waitcnt lgkmcnt(0)
	s_barrier
	ds_read_b128 v[150:153], v34 offset:18432
	ds_read_b128 v[154:157], v34 offset:18464
	ds_read_b128 v[158:161], v34 offset:23040
	ds_read_b128 v[162:165], v34 offset:23072
	ds_read_b128 v[166:169], v148 offset:55296
	ds_read_b128 v[170:173], v148 offset:55328
	ds_read_b128 v[174:177], v148 offset:59904
	ds_read_b128 v[178:181], v148 offset:59936
	s_setprio 1
	s_waitcnt lgkmcnt(3)
	v_mfma_f32_32x32x16_f16 v[0:15], v[150:153], v[166:169], v[0:15]
	s_waitcnt lgkmcnt(1)
	v_mfma_f32_32x32x16_f16 v[52:67], v[150:153], v[174:177], v[52:67]
	v_mfma_f32_32x32x16_f16 v[36:51], v[158:161], v[166:169], v[36:51]
	v_mfma_f32_32x32x16_f16 v[16:31], v[158:161], v[174:177], v[16:31]
	s_setprio 0
	ds_read_b128 v[150:153], v34 offset:18496
	ds_read_b128 v[158:161], v34 offset:23104
	ds_read_b128 v[166:169], v148 offset:55360
	ds_read_b128 v[174:177], v148 offset:59968
	s_setprio 1
	v_mfma_f32_32x32x16_f16 v[0:15], v[154:157], v[170:173], v[0:15]
	s_waitcnt lgkmcnt(4)
	v_mfma_f32_32x32x16_f16 v[52:67], v[154:157], v[178:181], v[52:67]
	v_mfma_f32_32x32x16_f16 v[36:51], v[162:165], v[170:173], v[36:51]
	v_mfma_f32_32x32x16_f16 v[16:31], v[162:165], v[178:181], v[16:31]
	s_setprio 0
	ds_read_b128 v[154:157], v34 offset:18528
	ds_read_b128 v[162:165], v34 offset:23136
	ds_read_b128 v[170:173], v148 offset:55392
	ds_read_b128 v[178:181], v148 offset:60000
	s_setprio 1
	s_waitcnt lgkmcnt(5)
	v_mfma_f32_32x32x16_f16 v[0:15], v[150:153], v[166:169], v[0:15]
	s_waitcnt lgkmcnt(4)
	v_mfma_f32_32x32x16_f16 v[52:67], v[150:153], v[174:177], v[52:67]
	v_mfma_f32_32x32x16_f16 v[36:51], v[158:161], v[166:169], v[36:51]
	v_mfma_f32_32x32x16_f16 v[16:31], v[158:161], v[174:177], v[16:31]
	s_setprio 0
	s_setprio 1
	s_waitcnt lgkmcnt(1)
	v_mfma_f32_32x32x16_f16 v[0:15], v[154:157], v[170:173], v[0:15]
	s_waitcnt lgkmcnt(0)
	v_mfma_f32_32x32x16_f16 v[52:67], v[154:157], v[178:181], v[52:67]
	v_mfma_f32_32x32x16_f16 v[36:51], v[162:165], v[170:173], v[36:51]
	v_mfma_f32_32x32x16_f16 v[16:31], v[162:165], v[178:181], v[16:31]
	s_setprio 0
	s_cmp_gt_u32 s12, 13
	s_cselect_b64 s[14:15], -1, 0
	s_and_b64 vcc, exec, s[14:15]
	s_cbranch_vccnz .LBB0_239
	ds_write_b128 v147, v[104:107]
	ds_write_b128 v147, v[72:75] offset:36864
	ds_write_b128 v147, v[112:115] offset:4608
	ds_write_b128 v147, v[84:87] offset:41472
	ds_write_b128 v147, v[92:95] offset:9216
	ds_write_b128 v147, v[120:123] offset:46080
	s_waitcnt vmcnt(8)
	ds_write_b128 v147, v[128:131] offset:13824
	ds_write_b128 v147, v[96:99] offset:50688
	s_branch .LBB0_239

; #define LAS __attribute__((address_space(3)))
; __global__ void __launch_bounds__(256, 2) mk(Params p_unused, int lo, int hi) {
;     extern __shared__ __attribute__((aligned(16))) char smem[];
;     cg::grid_group grid = cg::this_grid();
;     volatile LAS unsigned* xst = (volatile LAS unsigned*)(smem + RS_OFF + 512);
;     if (threadIdx.x == 0) { xst[0] = 0u; xst[1] = 0u; xst[2] = 0u; xst[3] = 0u; }
;     __syncthreads();
	.amdhsa_kernel _Z2mk6Paramsii
		.amdhsa_group_segment_fixed_size 0
		.amdhsa_private_segment_fixed_size 0
		.amdhsa_kernarg_size 496
		.amdhsa_user_sgpr_count 2
		.amdhsa_user_sgpr_dispatch_ptr 0
		.amdhsa_user_sgpr_queue_ptr 0
		.amdhsa_user_sgpr_kernarg_segment_ptr 1
		.amdhsa_user_sgpr_dispatch_id 0
		.amdhsa_user_sgpr_kernarg_preload_length 0
		.amdhsa_user_sgpr_kernarg_preload_offset 0
		.amdhsa_user_sgpr_private_segment_size 0
		.amdhsa_uses_dynamic_stack 0
		.amdhsa_enable_private_segment 0
		.amdhsa_system_sgpr_workgroup_id_x 1
		.amdhsa_system_sgpr_workgroup_id_y 0
		.amdhsa_system_sgpr_workgroup_id_z 0
		.amdhsa_system_sgpr_workgroup_info 0
		.amdhsa_system_vgpr_workitem_id 2
		.amdhsa_next_free_vgpr 248
		.amdhsa_next_free_sgpr 102
		.amdhsa_accum_offset 248
		.amdhsa_reserve_vcc 1
		.amdhsa_float_round_mode_32 0
		.amdhsa_float_round_mode_16_64 0
		.amdhsa_float_denorm_mode_32 3
		.amdhsa_float_denorm_mode_16_64 3
		.amdhsa_dx10_clamp 1
		.amdhsa_ieee_mode 1
		.amdhsa_fp16_overflow 0
		.amdhsa_tg_split 0
		.amdhsa_exception_fp_ieee_invalid_op 0
		.amdhsa_exception_fp_denorm_src 0
		.amdhsa_exception_fp_ieee_div_zero 0
		.amdhsa_exception_fp_ieee_overflow 0
		.amdhsa_exception_fp_ieee_underflow 0
		.amdhsa_exception_fp_ieee_inexact 0
		.amdhsa_exception_int_div_zero 0
	.end_amdhsa_kernel

; #define LAS __attribute__((address_space(3)))
; __global__ void __launch_bounds__(256, 2) mk(Params p_unused, int lo, int hi) {
;     extern __shared__ __attribute__((aligned(16))) char smem[];
;     cg::grid_group grid = cg::this_grid();
;     volatile LAS unsigned* xst = (volatile LAS unsigned*)(smem + RS_OFF + 512);
;     if (threadIdx.x == 0) { xst[0] = 0u; xst[1] = 0u; xst[2] = 0u; xst[3] = 0u; }
;     __syncthreads();
amdhsa.kernels:
  - .agpr_count:     0
    .args:
      - .offset:         0
        .size:           232
        .value_kind:     by_value
      - .offset:         232
        .size:           4
        .value_kind:     by_value
      - .offset:         236
        .size:           4
        .value_kind:     by_value
      - .offset:         240
        .size:           4
        .value_kind:     hidden_block_count_x
      - .offset:         244
        .size:           4
        .value_kind:     hidden_block_count_y
      - .offset:         248
        .size:           4
        .value_kind:     hidden_block_count_z
      - .offset:         252
        .size:           2
        .value_kind:     hidden_group_size_x
      - .offset:         254
        .size:           2
        .value_kind:     hidden_group_size_y
      - .offset:         256
        .size:           2
        .value_kind:     hidden_group_size_z
      - .offset:         258
        .size:           2
        .value_kind:     hidden_remainder_x
      - .offset:         260
        .size:           2
        .value_kind:     hidden_remainder_y
      - .offset:         262
        .size:           2
        .value_kind:     hidden_remainder_z
      - .offset:         280
        .size:           8
        .value_kind:     hidden_global_offset_x
      - .offset:         288
        .size:           8
        .value_kind:     hidden_global_offset_y
      - .offset:         296
        .size:           8
        .value_kind:     hidden_global_offset_z
      - .offset:         304
        .size:           2
        .value_kind:     hidden_grid_dims
      - .offset:         328
        .size:           8
        .value_kind:     hidden_multigrid_sync_arg
      - .offset:         360
        .size:           4
        .value_kind:     hidden_dynamic_lds_size
    .group_segment_fixed_size: 0
    .kernarg_segment_align: 8
    .kernarg_segment_size: 496
    .language:       OpenCL C
    .language_version:
      - 2
      - 0
    .max_flat_workgroup_size: 256
    .name:           _Z2mk6Paramsii
    .private_segment_fixed_size: 0
    .sgpr_count:     108
    .sgpr_spill_count: 128
    .symbol:         _Z2mk6Paramsii.kd
    .uniform_work_group_size: 1
    .uses_dynamic_stack: false
    .vgpr_count:     248
    .vgpr_spill_count: 0
    .wavefront_size: 64
